# phase-0 outputs write-through, no L2 writeback at barrier 1
# baseline (speedup 1.0000x reference)
.LBB0_7:
	v_and_b32_e32 v3, 0x3ff, v2
	v_mul_u32_u24_e32 v3, 0x1008, v3
	v_ashrrev_i32_e32 v8, 10, v2
	v_lshlrev_b32_e32 v6, 2, v3
	v_ashrrev_i32_e32 v9, 31, v8
	v_lshl_add_u64 v[10:11], s[56:57], 0, v[6:7]
	v_lshl_add_u64 v[8:9], v[8:9], 2, v[10:11]
	v_add_co_u32_e32 v8, vcc, 0x2000, v8
	v_add_u32_e32 v2, s6, v2
	s_nop 0
	v_addc_co_u32_e32 v9, vcc, 0, v9, vcc
	global_load_dword v3, v[8:9], off
	v_cmp_lt_i32_e32 vcc, s7, v2
	s_or_b64 s[4:5], vcc, s[4:5]
	s_waitcnt vmcnt(0)
	global_store_dword v[4:5], v3, off sc1
	v_lshl_add_u64 v[4:5], v[4:5], 0, s[2:3]
	s_andn2_b64 exec, exec, s[4:5]
	s_cbranch_execnz .LBB0_7
.LBB0_8:
	s_or_b64 exec, exec, s[0:1]
	s_add_u32 s2, s82, 0xb10000
	s_addc_u32 s3, s83, 0
	s_cmpk_lt_i32 s64, 0xc0
	s_cbranch_scc0 .LBB0_12
	s_and_b32 s4, s64, 3
	s_ashr_i32 s1, s8, 1
	s_lshl_b32 s5, s64, 4
	s_lshl_b32 s0, s4, 8
	s_andn2_b32 s1, s1, 31
	v_bfi_b32 v4, 63, v1, s5
	v_mov_b32_e32 v2, s50
	v_mov_b32_e32 v3, s51
	s_add_i32 s0, s1, s0
	v_ashrrev_i32_e32 v5, 31, v4
	v_lshl_add_u64 v[2:3], v[4:5], 2, v[2:3]
	v_mov_b32_e32 v44, 0x3000
	s_or_b32 s7, s0, 1
	s_ashr_i32 s1, s0, 31
	v_mad_i64_i32 v[6:7], s[10:11], s7, v44, v[2:3]
	s_or_b32 s7, s0, 2
	v_mad_i64_i32 v[4:5], s[10:11], s0, v44, v[2:3]
	v_mad_i64_i32 v[8:9], s[10:11], s7, v44, v[2:3]
	s_or_b32 s7, s0, 3
	s_or_b32 s9, s0, 4
	s_or_b32 s12, s0, 5
	s_or_b32 s13, s0, 6
	s_or_b32 s14, s0, 7
	s_or_b32 s15, s0, 8
	s_or_b32 s16, s0, 9
	s_or_b32 s17, s0, 10
	s_or_b32 s18, s0, 11
	s_or_b32 s19, s0, 12
	s_or_b32 s20, s0, 13
	s_or_b32 s21, s0, 14
	s_or_b32 s22, s0, 15
	s_or_b32 s23, s0, 16
	s_or_b32 s24, s0, 17
	s_or_b32 s25, s0, 18
	s_or_b32 s26, s0, 19
	s_or_b32 s27, s0, 20
	s_or_b32 s28, s0, 21
	s_or_b32 s29, s0, 22
	s_or_b32 s30, s0, 23
	s_or_b32 s31, s0, 24
	s_or_b32 s34, s0, 25
	s_or_b32 s35, s0, 26
	s_or_b32 s36, s0, 27
	s_or_b32 s37, s0, 28
	s_or_b32 s38, s0, 29
	s_or_b32 s39, s0, 30
	s_or_b32 s40, s0, 31
	s_lshl_b64 s[0:1], s[0:1], 2
	s_add_u32 s0, s46, s0
	s_addc_u32 s1, s47, s1
	v_mov_b32_e32 v46, 0
	global_load_dwordx4 v[14:17], v46, s[0:1] offset:16
	global_load_dwordx4 v[18:21], v46, s[0:1]
	v_mad_i64_i32 v[10:11], s[10:11], s7, v44, v[2:3]
	v_mad_i64_i32 v[12:13], s[10:11], s9, v44, v[2:3]
	v_mad_i64_i32 v[22:23], s[10:11], s12, v44, v[2:3]
	v_mad_i64_i32 v[24:25], s[10:11], s13, v44, v[2:3]
	v_mad_i64_i32 v[26:27], s[10:11], s14, v44, v[2:3]
	global_load_dword v47, v[4:5], off nt
	global_load_dword v48, v[6:7], off nt
	global_load_dword v49, v[8:9], off nt
	global_load_dword v50, v[10:11], off nt
	global_load_dword v51, v[12:13], off nt
	global_load_dword v52, v[22:23], off nt
	global_load_dword v53, v[24:25], off nt
	global_load_dword v54, v[26:27], off nt
	v_mad_i64_i32 v[4:5], s[10:11], s15, v44, v[2:3]
	v_mad_i64_i32 v[10:11], s[10:11], s18, v44, v[2:3]
	v_mad_i64_i32 v[12:13], s[10:11], s19, v44, v[2:3]
	v_mad_i64_i32 v[6:7], s[10:11], s16, v44, v[2:3]
	v_mad_i64_i32 v[8:9], s[10:11], s17, v44, v[2:3]
	v_mad_i64_i32 v[22:23], s[10:11], s20, v44, v[2:3]
	v_mad_i64_i32 v[24:25], s[10:11], s21, v44, v[2:3]
	global_load_dword v55, v[4:5], off nt
	global_load_dword v56, v[6:7], off nt
	global_load_dword v57, v[8:9], off nt
	global_load_dword v58, v[10:11], off nt
	global_load_dword v59, v[12:13], off nt
	global_load_dword v60, v[22:23], off nt
	global_load_dword v61, v[24:25], off nt
	v_mad_i64_i32 v[10:11], s[10:11], s26, v44, v[2:3]
	v_mad_i64_i32 v[12:13], s[10:11], s27, v44, v[2:3]
	v_mad_i64_i32 v[4:5], s[10:11], s23, v44, v[2:3]
	v_mad_i64_i32 v[6:7], s[10:11], s24, v44, v[2:3]
	v_mad_i64_i32 v[8:9], s[10:11], s25, v44, v[2:3]
	v_mad_i64_i32 v[30:31], s[10:11], s28, v44, v[2:3]
	v_mad_i64_i32 v[32:33], s[10:11], s29, v44, v[2:3]
	v_mad_i64_i32 v[34:35], s[10:11], s30, v44, v[2:3]
	global_load_dwordx4 v[22:25], v46, s[0:1] offset:48
	global_load_dwordx4 v[26:29], v46, s[0:1] offset:32
	global_load_dword v62, v[4:5], off nt
	global_load_dword v63, v[6:7], off nt
	global_load_dword v64, v[8:9], off nt
	global_load_dword v65, v[10:11], off nt
	s_nop 0
	global_load_dword v12, v[12:13], off nt
	s_nop 0
	global_load_dword v13, v[30:31], off nt
	global_load_dword v10, v[32:33], off nt
	global_load_dword v11, v[34:35], off nt
	v_mad_i64_i32 v[38:39], s[10:11], s22, v44, v[2:3]
	v_mad_i64_i32 v[4:5], s[10:11], s31, v44, v[2:3]
	v_mad_i64_i32 v[30:31], s[10:11], s34, v44, v[2:3]
	v_mad_i64_i32 v[32:33], s[10:11], s35, v44, v[2:3]
	v_mad_i64_i32 v[34:35], s[10:11], s36, v44, v[2:3]
	v_mad_i64_i32 v[36:37], s[10:11], s37, v44, v[2:3]
	v_mad_i64_i32 v[40:41], s[10:11], s38, v44, v[2:3]
	v_mad_i64_i32 v[42:43], s[10:11], s39, v44, v[2:3]
	v_mad_i64_i32 v[44:45], s[10:11], s40, v44, v[2:3]
	v_cmp_gt_i32_e32 vcc, 64, v1
	s_waitcnt vmcnt(25)
	v_mul_f32_e32 v6, 0xbfb8aa3b, v18
	v_exp_f32_e32 v6, v6
	s_nop 0
	v_add_f32_e32 v2, 1.0, v6
	v_rcp_f32_e32 v66, v2
	v_mul_f32_e32 v2, 0xbfb8aa3b, v19
	v_exp_f32_e32 v67, v2
	global_load_dword v8, v[4:5], off nt
	global_load_dword v9, v[30:31], off nt
	global_load_dword v6, v[32:33], off nt
	global_load_dword v7, v[34:35], off nt
	s_nop 0
	global_load_dword v4, v[36:37], off nt
	global_load_dword v5, v[40:41], off nt
	global_load_dword v2, v[42:43], off nt
	global_load_dword v3, v[44:45], off nt
	v_mul_f32_e32 v31, 0xbfb8aa3b, v20
	v_exp_f32_e32 v31, v31
	v_add_f32_e32 v30, 1.0, v67
	v_rcp_f32_e32 v30, v30
	v_mul_f32_e32 v18, v18, v66
	s_waitcnt vmcnt(32)
	v_fma_f32 v40, v47, v18, 0
	v_and_b32_e32 v41, 63, v1
	v_mul_f32_e32 v18, v19, v30
	s_waitcnt vmcnt(31)
	v_fmac_f32_e32 v40, v48, v18
	v_add_f32_e32 v18, 1.0, v31
	v_rcp_f32_e32 v18, v18
	v_mul_f32_e32 v19, 0xbfb8aa3b, v21
	v_exp_f32_e32 v19, v19
	global_load_dwordx4 v[30:33], v46, s[0:1] offset:64
	global_load_dwordx4 v[34:37], v46, s[0:1] offset:80
	v_mul_f32_e32 v18, v20, v18
	s_waitcnt vmcnt(32)
	v_fmac_f32_e32 v40, v49, v18
	v_add_f32_e32 v18, 1.0, v19
	v_mul_f32_e32 v19, 0xbfb8aa3b, v14
	v_exp_f32_e32 v19, v19
	v_rcp_f32_e32 v18, v18
	global_load_dword v38, v[38:39], off nt
	v_mul_f32_e32 v20, 0xbfb8aa3b, v15
	v_add_f32_e32 v19, 1.0, v19
	v_rcp_f32_e32 v19, v19
	v_exp_f32_e32 v20, v20
	v_mul_f32_e32 v18, v21, v18
	s_waitcnt vmcnt(32)
	v_fmac_f32_e32 v40, v50, v18
	v_mul_f32_e32 v14, v14, v19
	s_waitcnt vmcnt(31)
	v_fmac_f32_e32 v40, v51, v14
	v_add_f32_e32 v14, 1.0, v20
	v_mul_f32_e32 v18, 0xbfb8aa3b, v16
	v_rcp_f32_e32 v14, v14
	v_exp_f32_e32 v18, v18
	v_mul_f32_e32 v19, 0xbfb8aa3b, v17
	v_exp_f32_e32 v19, v19
	v_mul_f32_e32 v14, v15, v14
	v_add_f32_e32 v15, 1.0, v18
	v_rcp_f32_e32 v15, v15
	v_add_f32_e32 v18, 1.0, v19
	v_rcp_f32_e32 v18, v18
	s_waitcnt vmcnt(30)
	v_fmac_f32_e32 v40, v52, v14
	v_mul_f32_e32 v14, v16, v15
	s_waitcnt vmcnt(19)
	v_mul_f32_e32 v15, 0xbfb8aa3b, v26
	v_exp_f32_e32 v15, v15
	v_mul_f32_e32 v16, 0xbfb8aa3b, v27
	v_exp_f32_e32 v16, v16
	v_fmac_f32_e32 v40, v53, v14
	v_mul_f32_e32 v14, v17, v18
	v_fmac_f32_e32 v40, v54, v14
	v_add_f32_e32 v14, 1.0, v15
	v_rcp_f32_e32 v14, v14
	v_add_f32_e32 v15, 1.0, v16
	v_mul_f32_e32 v16, 0xbfb8aa3b, v28
	v_exp_f32_e32 v16, v16
	v_rcp_f32_e32 v15, v15
	v_mul_f32_e32 v14, v26, v14
	v_fmac_f32_e32 v40, v55, v14
	v_add_f32_e32 v14, 1.0, v16
	v_mul_f32_e32 v26, v27, v15
	v_rcp_f32_e32 v27, v14
	global_load_dwordx4 v[14:17], v46, s[0:1] offset:112
	global_load_dwordx4 v[18:21], v46, s[0:1] offset:96
	v_mul_f32_e32 v39, 0xbfb8aa3b, v29
	v_exp_f32_e32 v39, v39
	v_fmac_f32_e32 v40, v56, v26
	v_mul_f32_e32 v26, v28, v27
	v_mul_f32_e32 v27, 0xbfb8aa3b, v22
	v_exp_f32_e32 v27, v27
	v_mul_f32_e32 v28, 0xbfb8aa3b, v23
	v_exp_f32_e32 v28, v28
	v_fmac_f32_e32 v40, v57, v26
	v_add_f32_e32 v26, 1.0, v39
	v_rcp_f32_e32 v26, v26
	v_add_f32_e32 v27, 1.0, v27
	v_rcp_f32_e32 v27, v27
	v_add_f32_e32 v28, 1.0, v28
	v_rcp_f32_e32 v28, v28
	v_mul_f32_e32 v26, v29, v26
	v_fmac_f32_e32 v40, v58, v26
	v_mul_f32_e32 v22, v22, v27
	v_fmac_f32_e32 v40, v59, v22
	v_mul_f32_e32 v22, v23, v28
	v_mul_f32_e32 v23, 0xbfb8aa3b, v24
	v_exp_f32_e32 v23, v23
	v_mul_f32_e32 v26, 0xbfb8aa3b, v25
	v_exp_f32_e32 v26, v26
	v_fmac_f32_e32 v40, v60, v22
	v_add_f32_e32 v22, 1.0, v23
	v_rcp_f32_e32 v22, v22
	v_add_f32_e32 v23, 1.0, v26
	v_rcp_f32_e32 v23, v23
	s_and_b32 s0, s8, 0x3fffffc0
	v_mul_f32_e32 v22, v24, v22
	s_waitcnt vmcnt(4)
	v_mul_f32_e32 v26, 0xbfb8aa3b, v30
	v_exp_f32_e32 v26, v26
	v_fmac_f32_e32 v40, v61, v22
	v_mul_f32_e32 v22, v25, v23
	v_mul_f32_e32 v24, 0xbfb8aa3b, v31
	v_add_f32_e32 v23, 1.0, v26
	v_rcp_f32_e32 v23, v23
	v_exp_f32_e32 v24, v24
	s_waitcnt vmcnt(2)
	v_fmac_f32_e32 v40, v38, v22
	v_mul_f32_e32 v25, 0xbfb8aa3b, v37
	v_mul_f32_e32 v22, v30, v23
	v_mul_f32_e32 v23, 0xbfb8aa3b, v32
	v_fmac_f32_e32 v40, v62, v22
	v_add_f32_e32 v22, 1.0, v24
	v_exp_f32_e32 v23, v23
	v_mul_f32_e32 v24, 0xbfb8aa3b, v33
	v_exp_f32_e32 v24, v24
	v_rcp_f32_e32 v22, v22
	v_add_f32_e32 v23, 1.0, v23
	v_rcp_f32_e32 v23, v23
	v_add_f32_e32 v24, 1.0, v24
	v_rcp_f32_e32 v24, v24
	v_mul_f32_e32 v22, v31, v22
	v_fmac_f32_e32 v40, v63, v22
	v_mul_f32_e32 v22, v32, v23
	v_fmac_f32_e32 v40, v64, v22
	v_mul_f32_e32 v22, v33, v24
	v_mul_f32_e32 v23, 0xbfb8aa3b, v34
	v_mul_f32_e32 v24, 0xbfb8aa3b, v35
	v_exp_f32_e32 v23, v23
	v_exp_f32_e32 v24, v24
	v_fmac_f32_e32 v40, v65, v22
	v_exp_f32_e32 v25, v25
	v_add_f32_e32 v22, 1.0, v23
	v_add_f32_e32 v23, 1.0, v24
	v_mul_f32_e32 v24, 0xbfb8aa3b, v36
	v_exp_f32_e32 v24, v24
	v_rcp_f32_e32 v22, v22
	v_rcp_f32_e32 v23, v23
	v_add_f32_e32 v25, 1.0, v25
	v_add_f32_e32 v24, 1.0, v24
	v_rcp_f32_e32 v24, v24
	v_rcp_f32_e32 v25, v25
	v_pk_mul_f32 v[22:23], v[34:35], v[22:23]
	s_lshl_b32 s0, s0, 2
	v_pk_mul_f32 v[12:13], v[12:13], v[22:23]
	s_add_i32 s0, s0, 0
	v_add_f32_e32 v12, v40, v12
	v_add_f32_e32 v22, v12, v13
	v_pk_mul_f32 v[12:13], v[36:37], v[24:25]
	s_nop 0
	v_pk_mul_f32 v[10:11], v[10:11], v[12:13]
	s_waitcnt vmcnt(0)
	v_mul_f32_e32 v12, 0xbfb8aa3b, v18
	v_mul_f32_e32 v13, 0xbfb8aa3b, v19
	v_exp_f32_e32 v12, v12
	v_exp_f32_e32 v13, v13
	v_add_f32_e32 v10, v22, v10
	v_add_f32_e32 v22, v10, v11
	v_add_f32_e32 v10, 1.0, v12
	v_add_f32_e32 v11, 1.0, v13
	v_mul_f32_e32 v12, 0xbfb8aa3b, v20
	v_mul_f32_e32 v13, 0xbfb8aa3b, v21
	v_exp_f32_e32 v12, v12
	v_exp_f32_e32 v13, v13
	v_rcp_f32_e32 v10, v10
	v_rcp_f32_e32 v11, v11
	v_add_f32_e32 v12, 1.0, v12
	v_add_f32_e32 v13, 1.0, v13
	v_rcp_f32_e32 v12, v12
	v_rcp_f32_e32 v13, v13
	v_pk_mul_f32 v[10:11], v[18:19], v[10:11]
	s_nop 0
	v_pk_mul_f32 v[8:9], v[8:9], v[10:11]
	s_nop 0
	v_add_f32_e32 v8, v22, v8
	v_add_f32_e32 v10, v8, v9
	v_pk_mul_f32 v[8:9], v[20:21], v[12:13]
	s_nop 0
	v_pk_mul_f32 v[6:7], v[6:7], v[8:9]
	v_mul_f32_e32 v8, 0xbfb8aa3b, v14
	v_mul_f32_e32 v9, 0xbfb8aa3b, v15
	v_exp_f32_e32 v8, v8
	v_exp_f32_e32 v9, v9
	v_add_f32_e32 v6, v10, v6
	v_add_f32_e32 v10, v6, v7
	v_add_f32_e32 v6, 1.0, v8
	v_add_f32_e32 v7, 1.0, v9
	v_mul_f32_e32 v8, 0xbfb8aa3b, v16
	v_mul_f32_e32 v9, 0xbfb8aa3b, v17
	v_exp_f32_e32 v8, v8
	v_exp_f32_e32 v9, v9
	v_rcp_f32_e32 v6, v6
	v_rcp_f32_e32 v7, v7
	v_add_f32_e32 v8, 1.0, v8
	v_add_f32_e32 v9, 1.0, v9
	v_rcp_f32_e32 v8, v8
	v_rcp_f32_e32 v9, v9
	v_pk_mul_f32 v[6:7], v[14:15], v[6:7]
	s_nop 0
	v_pk_mul_f32 v[4:5], v[4:5], v[6:7]
	s_nop 0
	v_add_f32_e32 v4, v10, v4
	v_add_f32_e32 v6, v4, v5
	v_pk_mul_f32 v[4:5], v[16:17], v[8:9]
	s_nop 0
	v_pk_mul_f32 v[2:3], v[2:3], v[4:5]
	s_nop 0
	v_add_f32_e32 v2, v6, v2
	v_add_f32_e32 v2, v2, v3
	v_lshl_add_u32 v3, v41, 2, s0
	ds_write_b32 v3, v2
	s_waitcnt lgkmcnt(0)
	s_barrier
	s_and_saveexec_b64 s[0:1], vcc
	s_cbranch_execz .LBB0_11
	v_lshl_add_u32 v8, v1, 2, 0
	ds_read2st64_b32 v[2:3], v8 offset1:1
	ds_read2st64_b32 v[4:5], v8 offset0:2 offset1:3
	ds_read2st64_b32 v[6:7], v8 offset0:4 offset1:5
	ds_read2st64_b32 v[8:9], v8 offset0:6 offset1:7
	s_andn2_b32 s5, s5, 63
	s_mulk_i32 s4, 0xc00
	s_add_i32 s4, s4, s5
	s_waitcnt lgkmcnt(3)
	v_add_f32_e32 v2, 0, v2
	v_add_f32_e32 v2, v2, v3
	s_waitcnt lgkmcnt(2)
	v_add_f32_e32 v2, v2, v4
	v_add_f32_e32 v2, v2, v5
	s_waitcnt lgkmcnt(1)
	v_add_f32_e32 v2, v2, v6
	v_add_f32_e32 v2, v2, v7
	s_waitcnt lgkmcnt(0)
	v_add_f32_e32 v2, v2, v8
	v_add_f32_e32 v4, v2, v9
	v_add_u32_e32 v2, s4, v1
	v_ashrrev_i32_e32 v3, 31, v2
	v_lshl_add_u64 v[2:3], v[2:3], 2, s[2:3]
	global_store_dword v[2:3], v4, off sc1

.Lsplit1_nl:
.LBB0_44:
	s_andn2_saveexec_b64 s[8:9], s[8:9]
	s_cbranch_execz .LBB0_64
	s_mov_b64 s[8:9], exec
	buffer_inv sc1
	s_waitcnt lgkmcnt(0)
	s_waitcnt vmcnt(0)
	v_mbcnt_lo_u32_b32 v2, s8, 0
	v_mbcnt_hi_u32_b32 v2, s9, v2
	v_cmp_eq_u32_e32 vcc, 0, v2
	s_and_saveexec_b64 s[10:11], vcc
	s_cbranch_execz .LBB0_47
	s_bcnt1_i32_b64 s7, s[8:9]
	v_mov_b32_e32 v3, 0x7000
	v_mov_b32_e32 v4, s7
	global_atomic_add v3, v3, v4, s[82:83] offset:1024 sc0
